# attention pre-pass B: next row's 4 loads prefetched into a second register set at the top of each iteration (copied over at the next top), body waits removed
# baseline (speedup 1.0000x reference)
.LBB0_413:
	s_andn2_b64 vcc, exec, s[0:1]
	s_cbranch_vccnz .LBB0_426
	s_cmp_gt_i32 s20, 0x81ff
	s_cbranch_scc1 .LBB0_426
	s_waitcnt lgkmcnt(0)
	v_lshlrev_b32_e32 v1, 3, v190
	v_and_b32_e32 v4, 64, v174
	v_and_b32_e32 v3, 8, v1
	v_xor_b32_e32 v1, 1, v174
	v_add_u32_e32 v4, 64, v4
	v_cmp_lt_i32_e32 vcc, v1, v4
	v_lshrrev_b32_e32 v0, 3, v189
	v_and_b32_e32 v2, 7, v190
	v_cndmask_b32_e32 v1, v174, v1, vcc
	s_waitcnt vmcnt(0)
	v_lshlrev_b32_e32 v81, 2, v1
	v_xor_b32_e32 v1, 2, v174
	v_cmp_lt_i32_e32 vcc, v1, v4
	v_readlane_b32 s0, v254, 54
	v_lshlrev_b32_e32 v112, 5, v2
	v_cndmask_b32_e32 v1, v174, v1, vcc
	v_lshlrev_b32_e32 v82, 2, v1
	v_xor_b32_e32 v1, 4, v174
	v_cmp_lt_i32_e32 vcc, v1, v4
	v_mul_u32_u24_e32 v4, 0x60, v0
	v_lshlrev_b32_e32 v0, 5, v190
	v_cndmask_b32_e32 v1, v174, v1, vcc
	v_lshlrev_b32_e32 v83, 2, v1
	v_and_b32_e32 v1, 2, v190
	v_cmp_eq_u32_e64 s[38:39], 0, v1
	v_readlane_b32 s1, v254, 55
	v_and_b32_e32 v0, 0x60, v0
	v_mov_b32_e32 v1, v113
	v_lshl_add_u64 v[16:17], s[0:1], 0, v[112:113]
	v_lshl_add_u64 v[18:19], s[0:1], 0, v[0:1]
	v_readlane_b32 s0, v254, 56
	v_readlane_b32 s1, v254, 57
	v_cmp_eq_u32_e32 vcc, 0, v3
	s_ashr_i32 s21, s20, 31
	v_lshl_add_u64 v[22:23], s[0:1], 0, v[0:1]
	v_mov_b32_e32 v0, 0x3f5a1371
	v_mov_b32_e32 v1, 0x3fc45f30
	v_cndmask_b32_e32 v25, v0, v1, vcc
	v_mov_b32_e32 v0, 0x305e714c
	v_mov_b32_e32 v1, 0x6dc9c883
	v_cndmask_b32_e32 v24, v0, v1, vcc
	v_mov_b32_e32 v0, 0x3f4d53c1
	v_mov_b32_e32 v1, 0x3fb6e96e
	v_cndmask_b32_e32 v27, v0, v1, vcc
	v_mov_b32_e32 v0, 0x3bd66b8
	v_mov_b32_e32 v1, 0xcaebf83f
	v_cndmask_b32_e32 v26, v0, v1, vcc
	v_mov_b32_e32 v0, 0x3f407deb
	v_mov_b32_e32 v1, 0x3fa9c4c0
	v_cndmask_b32_e32 v29, v0, v1, vcc
	v_mov_b32_e32 v0, 0x99a0e17a
	v_mov_b32_e32 v1, 0x200b604f
	v_cndmask_b32_e32 v28, v0, v1, vcc
	v_mov_b32_e32 v0, 0x3f328c52
	v_mov_b32_e32 v1, 0x3f9cfb40
	v_cndmask_b32_e32 v31, v0, v1, vcc
	v_mov_b32_e32 v0, 0xe12d9f9
	v_mov_b32_e32 v1, 0x35fd7496
	v_cndmask_b32_e32 v30, v0, v1, vcc
	v_mov_b32_e32 v0, 0x3f24dc5a
	v_mov_b32_e32 v1, 0x3f904c26
	v_cndmask_b32_e32 v33, v0, v1, vcc
	v_mov_b32_e32 v0, 0x8d185aa3
	v_mov_b32_e32 v1, 0xbe3b06cf
	v_cndmask_b32_e32 v32, v0, v1, vcc
	v_mov_b32_e32 v0, 0x3f177634
	v_mov_b32_e32 v1, 0x3f825458
	v_cndmask_b32_e32 v35, v0, v1, vcc
	v_mov_b32_e32 v0, 0x2fdebc6
	v_mov_b32_e32 v1, 0xa2566033
	v_lshl_add_u64 v[20:21], s[0:1], 0, v[112:113]
	v_cndmask_b32_e32 v34, v0, v1, vcc
	v_mov_b32_e32 v0, 0x3f0a6312
	v_mov_b32_e32 v1, 0x3f749d66
	s_lshl_b64 s[0:1], s[20:21], 9
	v_readlane_b32 s2, v251, 49
	v_cmp_gt_u32_e64 s[36:37], 4, v2
	v_cndmask_b32_e32 v37, v0, v1, vcc
	v_mov_b32_e32 v0, 0x800919d9
	v_lshlrev_b32_e32 v112, 4, v2
	v_bfe_u32 v2, v190, 3, 3
	v_readlane_b32 s3, v251, 50
	s_add_u32 s0, s2, s0
	v_cndmask_b32_e32 v36, v250, v0, vcc
	v_lshlrev_b32_e32 v0, 6, v2
	v_mov_b32_e32 v1, v113
	s_addc_u32 s1, s3, s1
	v_lshl_add_u64 v[40:41], s[0:1], 0, v[0:1]
	s_mul_i32 s0, s20, 0x1200
	v_readlane_b32 s2, v253, 19
	s_mul_hi_i32 s1, s20, 0x1200
	s_add_u32 s0, s2, s0
	v_readlane_b32 s2, v253, 20
	s_addc_u32 s1, s2, s1
	s_mul_i32 s2, s20, 0x600
	s_mul_hi_i32 s3, s20, 0x600
	s_add_u32 s2, s70, s2
	v_lshlrev_b32_e32 v0, 1, v4
	s_addc_u32 s3, s71, s3
	v_lshl_add_u64 v[42:43], s[2:3], 0, v[0:1]
	s_lshl_b64 s[2:3], s[20:21], 11
	v_readlane_b32 s4, v251, 47
	v_readlane_b32 s5, v251, 48
	s_add_u32 s2, s4, s2
	v_lshlrev_b32_e32 v0, 8, v2
	s_addc_u32 s3, s5, s3
	v_cndmask_b32_e32 v39, v182, v183, vcc
	v_cndmask_b32_e32 v38, v184, v185, vcc
	v_lshl_add_u64 v[44:45], s[2:3], 0, v[0:1]
	s_mov_b32 s4, s20
	v_readlane_b32 s5, v253, 39
	v_readlane_b32 s14, v253, 42
	global_load_dwordx4 v[192:195], v[18:19], off offset:256
	global_load_dwordx4 v[196:199], v[18:19], off offset:272
	global_load_dwordx4 v[200:203], v[16:17], off offset:16
	global_load_dwordx4 v[204:207], v[16:17], off
	global_load_dwordx4 v[208:211], v[22:23], off offset:256
	global_load_dwordx4 v[212:215], v[22:23], off offset:272
	global_load_dwordx4 v[216:219], v[20:21], off offset:16
	global_load_dwordx4 v[220:223], v[20:21], off
	v_lshl_add_u64 v[104:105], v[42:43], 0, v[112:113]
	s_mov_b64 s[2:3], 0x17360000
	v_lshl_add_u64 v[106:107], v[44:45], 0, v[112:113]
	v_lshl_add_u64 v[104:105], v[104:105], 0, s[2:3]
	v_lshl_add_u64 v[108:109], s[0:1], 0, v[112:113]
	v_mov_b32_e32 v92, 0
	v_mov_b32_e32 v93, 0
	v_mov_b32_e32 v94, 0
	v_mov_b32_e32 v95, 0
	global_load_dwordx4 v[88:91], v[104:105], off
	global_load_dwordx4 v[96:99], v[106:107], off
	v_mov_b32_e32 v100, 0
	v_mov_b32_e32 v101, 0
	v_mov_b32_e32 v102, 0
	v_mov_b32_e32 v103, 0
	s_and_saveexec_b64 vcc, s[36:37]
	global_load_dwordx4 v[92:95], v[104:105], off offset:128
	global_load_dwordx4 v[100:103], v[108:109], off
	s_or_b64 exec, exec, vcc
	s_waitcnt vmcnt(0)
	s_branch .LBB0_417

.LBB0_417:
	v_lshl_add_u64 v[62:63], v[42:43], 0, v[112:113]
	s_mov_b64 s[2:3], 0x17360000
	s_waitcnt lgkmcnt(0)
	v_lshl_add_u64 v[64:65], v[62:63], 0, s[2:3]
	s_waitcnt vmcnt(4)
	v_mov_b64_e32 v[0:1], v[88:89]
	v_mov_b64_e32 v[2:3], v[90:91]
	v_mov_b64_e32 v[8:9], v[92:93]
	v_mov_b64_e32 v[10:11], v[94:95]
	v_mov_b64_e32 v[228:229], v[96:97]
	v_mov_b64_e32 v[230:231], v[98:99]
	v_mov_b64_e32 v[232:233], v[100:101]
	v_mov_b64_e32 v[234:235], v[102:103]
	v_readlane_b32 s2, v253, 40
	v_readlane_b32 s100, v253, 21
	v_readlane_b32 s101, v253, 22
	s_nop 1
	s_add_i32 s2, s4, s2
	s_cmp_gt_i32 s2, 0x81ff
	s_cbranch_scc1 .Lpb_nopf
	v_lshl_add_u64 v[110:111], v[42:43], 0, s[12:13]
	v_lshl_add_u64 v[114:115], v[44:45], 0, s[100:101]
	s_add_u32 s100, s0, s14
	s_addc_u32 s101, s1, s5
	v_lshl_add_u64 v[104:105], v[110:111], 0, v[112:113]
	s_mov_b64 s[2:3], 0x17360000
	v_lshl_add_u64 v[106:107], v[114:115], 0, v[112:113]
	v_lshl_add_u64 v[104:105], v[104:105], 0, s[2:3]
	v_lshl_add_u64 v[108:109], s[100:101], 0, v[112:113]
	v_mov_b32_e32 v92, 0
	v_mov_b32_e32 v93, 0
	v_mov_b32_e32 v94, 0
	v_mov_b32_e32 v95, 0
	global_load_dwordx4 v[88:91], v[104:105], off
	global_load_dwordx4 v[96:99], v[106:107], off
	v_mov_b32_e32 v100, 0
	v_mov_b32_e32 v101, 0
	v_mov_b32_e32 v102, 0
	v_mov_b32_e32 v103, 0
	s_and_saveexec_b64 vcc, s[36:37]
	global_load_dwordx4 v[92:95], v[104:105], off offset:128
	global_load_dwordx4 v[100:103], v[108:109], off
	s_or_b64 exec, exec, vcc
.Lpb_nopf:
	s_mul_hi_i32 s2, s4, 0x7e07e07f
	s_lshr_b32 s3, s2, 31
	s_ashr_i32 s2, s2, 12
	s_add_i32 s2, s2, s3
	s_mulk_i32 s2, 0x2080
	s_sub_i32 s2, s4, s2
	s_max_i32 s2, s2, 0x70
	s_addk_i32 s2, 0xff90
	v_cvt_f64_u32_e32 v[4:5], s2
	v_mul_f64 v[6:7], v[24:25], v[4:5]
	v_floor_f64_e32 v[6:7], v[6:7]
	v_fma_f64 v[6:7], v[24:25], v[4:5], -v[6:7]
	v_cvt_f32_f64_e32 v6, v[6:7]
	v_cos_f32_e32 v84, v6
	v_sin_f32_e32 v85, v6
	v_mul_f64 v[6:7], v[26:27], v[4:5]
	v_floor_f64_e32 v[6:7], v[6:7]
	v_fma_f64 v[6:7], v[26:27], v[4:5], -v[6:7]
	v_cvt_f32_f64_e32 v6, v[6:7]
	v_cos_f32_e32 v46, v6
	v_sin_f32_e32 v49, v6
	v_mul_f64 v[6:7], v[28:29], v[4:5]
	v_floor_f64_e32 v[6:7], v[6:7]
	v_fma_f64 v[6:7], v[28:29], v[4:5], -v[6:7]
	v_cvt_f32_f64_e32 v6, v[6:7]
	v_cos_f32_e32 v50, v6
	v_sin_f32_e32 v52, v6
	v_mul_f64 v[6:7], v[30:31], v[4:5]
	v_floor_f64_e32 v[6:7], v[6:7]
	v_fma_f64 v[6:7], v[30:31], v[4:5], -v[6:7]
	v_cvt_f32_f64_e32 v6, v[6:7]
	v_cos_f32_e32 v51, v6
	v_sin_f32_e32 v53, v6
	v_mul_f64 v[6:7], v[32:33], v[4:5]
	v_floor_f64_e32 v[6:7], v[6:7]
	v_fma_f64 v[6:7], v[32:33], v[4:5], -v[6:7]
	v_cvt_f32_f64_e32 v6, v[6:7]
	v_cos_f32_e32 v54, v6
	v_sin_f32_e32 v56, v6
	v_mul_f64 v[6:7], v[34:35], v[4:5]
	v_floor_f64_e32 v[6:7], v[6:7]
	v_fma_f64 v[6:7], v[34:35], v[4:5], -v[6:7]
	v_cvt_f32_f64_e32 v6, v[6:7]
	v_cos_f32_e32 v55, v6
	v_sin_f32_e32 v57, v6
	v_mul_f64 v[6:7], v[36:37], v[4:5]
	v_floor_f64_e32 v[6:7], v[6:7]
	v_fma_f64 v[6:7], v[36:37], v[4:5], -v[6:7]
	v_cvt_f32_f64_e32 v6, v[6:7]
	v_cos_f32_e32 v58, v6
	v_sin_f32_e32 v60, v6
	v_mul_f64 v[6:7], v[38:39], v[4:5]
	v_floor_f64_e32 v[6:7], v[6:7]
	v_lshlrev_b32_e32 v72, 16, v0
	v_and_b32_e32 v47, 0xffff0000, v8
	v_fma_f64 v[4:5], v[38:39], v[4:5], -v[6:7]
	v_and_b32_e32 v73, 0xffff0000, v0
	v_lshlrev_b32_e32 v70, 16, v1
	v_and_b32_e32 v71, 0xffff0000, v1
	v_lshlrev_b32_e32 v14, 16, v8
	v_mul_f32_e32 v0, v72, v72
	v_mul_f32_e32 v1, v47, v47
	v_cvt_f32_f64_e32 v4, v[4:5]
	v_fmac_f32_e32 v0, v14, v14
	v_fmac_f32_e32 v1, v73, v73
	v_cos_f32_e32 v59, v4
	v_sin_f32_e32 v61, v4
	v_lshlrev_b32_e32 v68, 16, v2
	v_and_b32_e32 v69, 0xffff0000, v2
	v_lshlrev_b32_e32 v66, 16, v3
	v_and_b32_e32 v67, 0xffff0000, v3
	v_add_f32_e32 v8, v0, v1
	v_mov_b64_e32 v[4:5], v[192:193]
	v_mov_b64_e32 v[6:7], v[194:195]
	v_mov_b64_e32 v[0:1], v[196:197]
	v_mov_b64_e32 v[2:3], v[198:199]
	v_lshlrev_b32_e32 v76, 16, v9
	v_and_b32_e32 v77, 0xffff0000, v9
	v_mul_f32_e32 v9, v76, v76
	v_fmac_f32_e32 v9, v70, v70
	v_add_f32_e32 v8, v8, v9
	v_mul_f32_e32 v9, v77, v77
	v_fmac_f32_e32 v9, v71, v71
	v_lshlrev_b32_e32 v78, 16, v10
	v_and_b32_e32 v79, 0xffff0000, v10
	v_lshlrev_b32_e32 v74, 16, v11
	v_and_b32_e32 v75, 0xffff0000, v11
	v_add_f32_e32 v11, v8, v9
	v_pk_mul_f32 v[8:9], v[78:79], v[78:79]
	v_pk_mul_f32 v[12:13], v[74:75], v[74:75]
	v_pk_fma_f32 v[8:9], v[68:69], v[68:69], v[8:9]
	v_pk_fma_f32 v[12:13], v[66:67], v[66:67], v[12:13]
	v_add_f32_e32 v8, v11, v8
	v_add_f32_e32 v8, v8, v9
	v_add_f32_e32 v8, v8, v12
	v_add_f32_e32 v8, v8, v13
	ds_bpermute_b32 v9, v81, v8
	s_mov_b32 s2, 0x3e16c740
	s_waitcnt lgkmcnt(0)
	v_add_f32_e32 v8, v8, v9
	ds_bpermute_b32 v9, v82, v8
	s_waitcnt lgkmcnt(0)
	v_add_f32_e32 v8, v8, v9
	ds_bpermute_b32 v9, v83, v8
	s_waitcnt lgkmcnt(0)
	v_add_f32_e32 v8, v8, v9
	v_fmamk_f32 v8, v8, 0x3c2aaaab, v172
	v_rsq_f32_e32 v80, v8
	s_nop 0
	v_mul_f32_e32 v8, v80, v14
	v_pk_mul_f32 v[72:73], v[80:81], v[72:73] op_sel_hi:[0,1]
	v_mul_f32_e32 v4, v8, v4
	v_mov_b64_e32 v[8:9], v[200:201]
	v_mov_b64_e32 v[10:11], v[202:203]
	v_mov_b64_e32 v[12:13], v[204:205]
	v_mov_b64_e32 v[14:15], v[206:207]
	v_mul_f32_e32 v86, 0x3e16c740, v4
	v_mul_f32_e32 v4, v80, v47
	v_mul_f32_e32 v4, v4, v5
	v_mul_f32_e32 v48, 0x3e16c740, v4
	v_pk_mul_f32 v[4:5], v[80:81], v[70:71] op_sel_hi:[0,1]
	ds_bpermute_b32 v47, v82, v48
	v_pk_mul_f32 v[4:5], v[4:5], v[14:15]
	s_nop 0
	v_pk_mul_f32 v[14:15], v[4:5], s[2:3] op_sel_hi:[1,0]
	v_pk_mul_f32 v[4:5], v[80:81], v[76:77] op_sel_hi:[0,1]
	v_pk_mul_f32 v[4:5], v[4:5], v[6:7]
	v_pk_mul_f32 v[6:7], v[80:81], v[68:69] op_sel_hi:[0,1]
	v_pk_mul_f32 v[6:7], v[6:7], v[8:9]
	v_pk_mul_f32 v[12:13], v[72:73], v[12:13]
	v_pk_mul_f32 v[68:69], v[6:7], s[2:3] op_sel_hi:[1,0]
	v_pk_mul_f32 v[6:7], v[80:81], v[78:79] op_sel_hi:[0,1]
	v_pk_mul_f32 v[0:1], v[6:7], v[0:1]
	v_pk_mul_f32 v[6:7], v[80:81], v[66:67] op_sel_hi:[0,1]
	v_pk_mul_f32 v[6:7], v[6:7], v[10:11]
	v_pk_mul_f32 v[4:5], v[4:5], s[2:3] op_sel_hi:[1,0]
	v_pk_mul_f32 v[70:71], v[6:7], s[2:3] op_sel_hi:[1,0]
	v_pk_mul_f32 v[6:7], v[80:81], v[74:75] op_sel_hi:[0,1]
	v_pk_mul_f32 v[2:3], v[6:7], v[2:3]
	v_pk_mul_f32 v[0:1], v[0:1], s[2:3] op_sel_hi:[1,0]
	v_pk_mul_f32 v[8:9], v[2:3], s[2:3] op_sel_hi:[1,0]
	v_pk_mul_f32 v[72:73], v[12:13], s[2:3] op_sel_hi:[1,0]
	ds_bpermute_b32 v12, v82, v86
	ds_bpermute_b32 v2, v82, v4
	ds_bpermute_b32 v3, v82, v5
	ds_bpermute_b32 v6, v82, v0
	ds_bpermute_b32 v7, v82, v1
	ds_bpermute_b32 v10, v82, v8
	ds_bpermute_b32 v11, v82, v9
	v_cvt_pk_bf16_f32 v66, v72, v73
	v_cvt_pk_bf16_f32 v67, v14, v15
	v_cvt_pk_bf16_f32 v68, v68, v69
	v_cvt_pk_bf16_f32 v69, v70, v71
	global_store_dwordx4 v[64:65], v[66:69], off
	s_and_saveexec_b64 s[2:3], s[36:37]
	s_cbranch_execz .LBB0_421
	s_waitcnt lgkmcnt(0)
	v_pk_mul_f32 v[10:11], v[60:61], v[10:11]
	v_pk_mul_f32 v[6:7], v[56:57], v[6:7]
	v_pk_fma_f32 v[14:15], v[8:9], v[58:59], v[10:11] neg_lo:[0,0,1] neg_hi:[0,0,1]
	v_pk_fma_f32 v[8:9], v[8:9], v[58:59], v[10:11]
	s_nop 0
	v_cndmask_b32_e64 v10, v9, v15, s[38:39]
	v_cndmask_b32_e64 v11, v8, v14, s[38:39]
	v_pk_fma_f32 v[8:9], v[0:1], v[54:55], v[6:7] neg_lo:[0,0,1] neg_hi:[0,0,1]
	v_pk_fma_f32 v[0:1], v[0:1], v[54:55], v[6:7]
	s_nop 0
	v_cndmask_b32_e64 v6, v1, v9, s[38:39]
	v_cndmask_b32_e64 v7, v0, v8, s[38:39]
	v_pk_mul_f32 v[0:1], v[52:53], v[2:3]
	s_nop 0
	v_pk_fma_f32 v[2:3], v[4:5], v[50:51], v[0:1] neg_lo:[0,0,1] neg_hi:[0,0,1]
	v_pk_fma_f32 v[0:1], v[4:5], v[50:51], v[0:1]
	s_nop 0
	v_cndmask_b32_e64 v2, v0, v2, s[38:39]
	v_mul_f32_e32 v0, v85, v12
	v_cndmask_b32_e64 v3, v1, v3, s[38:39]
	v_cndmask_b32_e64 v4, v0, -v0, s[38:39]
	v_pk_mul_f32 v[0:1], v[48:49], v[46:47]
	v_fmac_f32_e32 v4, v86, v84
	v_sub_f32_e32 v5, v0, v1
	v_add_f32_e32 v0, v0, v1
	v_cndmask_b32_e64 v0, v0, v5, s[38:39]
	v_cvt_pk_bf16_f32 v0, v4, v0
	v_add_co_u32_e32 v4, vcc, 0x17360000, v62
	v_cvt_pk_bf16_f32 v1, v2, v3
	v_cvt_pk_bf16_f32 v2, v7, v6
	v_cvt_pk_bf16_f32 v3, v11, v10
	v_addc_co_u32_e32 v5, vcc, 0, v63, vcc
	global_store_dwordx4 v[4:5], v[0:3], off offset:128
